# static priority raised for waves 0-3 instead of waves 4-7 in the fast-path attention units (guide 7.4: try each half); on top of v18
# baseline (speedup 1.0000x reference)
; template<int THRL,int VM,bool NOMAX> __device__ __forceinline__ void attn_unit(const bf16*Qb,const bf16*__restrict__ Kh,const bf16*__restrict__ Vh,bf16*Ob,const int NT,const int sp,float*wscr,char*shm){
;   int tid_=threadIdx.x; asm volatile("":"+v"(tid_));
;   const int tid=tid_,lane=tid&63,r32=lane&31,hi=lane>>5; const int wid=__builtin_amdgcn_readfirstlane(tid>>6);
;   const bf16*Qw=Qb+(long)(wid*QBLK)*QOP;
;   const unsigned lds0=(unsigned)(uintptr_t)shm;
;   constexpr int LDS_WS_=LDS_V+3*VM*SLOTB, LDS_OST_=LDS_WS_+NW*64*4;
;   float*wsf=(float*)(shm+LDS_WS_)+wid*64;
;   const bf16*ksrc=Kh+(long)lane*KVP+wid*8;
;   const bf16*vsrc=Vh+(long)(16*(wid&3)+(lane>>2))*KVP+(wid>>2)*32+(lane&3)*8;
;   const unsigned kdst=lds0+LDS_K+wid*1024, vdst=lds0+LDS_V+wid*1024;
;     ...
;   const int vb0=(int)(lds0+LDS_V)+((lane>>4)&1)*32+(lane&3)*8+(4*hi+((lane&15)>>2))*64;
;   const char*Kbase=shm+LDS_K; bf16x8 kf[8];
;   const lds_cptr shm3=(lds_cptr)shm; const lds_cptr kp0=shm3+LDS_K+hi*1024+r32*16; const lds_cptr vp0=shm3+LDS_V+((lane>>4)&1)*32+(lane&3)*8+(4*hi+((lane&15)>>2))*64;
;   if(wid>=4)__builtin_amdgcn_s_setprio(1);
.LBB0_860:
	v_mov_b32_e32 v32, v210
	s_nop 0
	v_readfirstlane_b32 s34, v32
	s_ashr_i32 s85, s34, 6
	s_cmp_lt_i32 s85, 4
	s_cbranch_scc0 .LBB0_862
	s_setprio 1

; template<int THRL,int VM,bool NOMAX> __device__ __forceinline__ void attn_unit(const bf16*Qb,const bf16*__restrict__ Kh,const bf16*__restrict__ Vh,bf16*Ob,const int NT,const int sp,float*wscr,char*shm){
;   int tid_=threadIdx.x; asm volatile("":"+v"(tid_));
;   const int tid=tid_,lane=tid&63,r32=lane&31,hi=lane>>5; const int wid=__builtin_amdgcn_readfirstlane(tid>>6);
;   const bf16*Qw=Qb+(long)(wid*QBLK)*QOP;
;   const unsigned lds0=(unsigned)(uintptr_t)shm;
;   constexpr int LDS_WS_=LDS_V+3*VM*SLOTB, LDS_OST_=LDS_WS_+NW*64*4;
;   float*wsf=(float*)(shm+LDS_WS_)+wid*64;
;   const bf16*ksrc=Kh+(long)lane*KVP+wid*8;
;   const bf16*vsrc=Vh+(long)(16*(wid&3)+(lane>>2))*KVP+(wid>>2)*32+(lane&3)*8;
;   const unsigned kdst=lds0+LDS_K+wid*1024, vdst=lds0+LDS_V+wid*1024;
;     ...
;   const int vb0=(int)(lds0+LDS_V)+((lane>>4)&1)*32+(lane&3)*8+(4*hi+((lane&15)>>2))*64;
;   const char*Kbase=shm+LDS_K; bf16x8 kf[8];
;   const lds_cptr shm3=(lds_cptr)shm; const lds_cptr kp0=shm3+LDS_K+hi*1024+r32*16; const lds_cptr vp0=shm3+LDS_V+((lane>>4)&1)*32+(lane&3)*8+(4*hi+((lane&15)>>2))*64;
;   if(wid>=4)__builtin_amdgcn_s_setprio(1);
.LBB0_879:
	v_mov_b32_e32 v48, v210
	s_nop 0
	v_readfirstlane_b32 s29, v48
	s_ashr_i32 s28, s29, 6
	s_cmp_lt_i32 s28, 4
	s_cbranch_scc0 .LBB0_881
	s_setprio 1

; template<int THRL,int VM,bool NOMAX> __device__ __forceinline__ void attn_unit(const bf16*Qb,const bf16*__restrict__ Kh,const bf16*__restrict__ Vh,bf16*Ob,const int NT,const int sp,float*wscr,char*shm){
;   int tid_=threadIdx.x; asm volatile("":"+v"(tid_));
;   const int tid=tid_,lane=tid&63,r32=lane&31,hi=lane>>5; const int wid=__builtin_amdgcn_readfirstlane(tid>>6);
;   const bf16*Qw=Qb+(long)(wid*QBLK)*QOP;
;   const unsigned lds0=(unsigned)(uintptr_t)shm;
;   constexpr int LDS_WS_=LDS_V+3*VM*SLOTB, LDS_OST_=LDS_WS_+NW*64*4;
;   float*wsf=(float*)(shm+LDS_WS_)+wid*64;
;   const bf16*ksrc=Kh+(long)lane*KVP+wid*8;
;   const bf16*vsrc=Vh+(long)(16*(wid&3)+(lane>>2))*KVP+(wid>>2)*32+(lane&3)*8;
;   const unsigned kdst=lds0+LDS_K+wid*1024, vdst=lds0+LDS_V+wid*1024;
;     ...
;   const int vb0=(int)(lds0+LDS_V)+((lane>>4)&1)*32+(lane&3)*8+(4*hi+((lane&15)>>2))*64;
;   const char*Kbase=shm+LDS_K; bf16x8 kf[8];
;   const lds_cptr shm3=(lds_cptr)shm; const lds_cptr kp0=shm3+LDS_K+hi*1024+r32*16; const lds_cptr vp0=shm3+LDS_V+((lane>>4)&1)*32+(lane&3)*8+(4*hi+((lane&15)>>2))*64;
;   if(wid>=4)__builtin_amdgcn_s_setprio(1);
.LBB0_888:
	v_mov_b32_e32 v48, v210
	s_nop 0
	v_readfirstlane_b32 s19, v48
	s_ashr_i32 s18, s19, 6
	s_cmp_lt_i32 s18, 4
	s_cbranch_scc0 .LBB0_890
	s_setprio 1
